# guard verdict cached in a spare lane of the SGPR-spill VGPR: each barrier reads it with v_readlane instead of loading the flag words
# speedup vs baseline: 1.0054x; 1.0054x over previous
; DI void grid_barrier(const Ctx& c, unsigned idx) {
;     ...
;   asm volatile("s_waitcnt vmcnt(0)" ::: "memory");
;   __syncthreads();
;   if (TIDX == 0) {
;     unsigned* bar = (unsigned*)(p.ws + OFF_BAR);
;     const unsigned G = gridDim.x, grp = blockIdx.x & 7u;
;     const unsigned gsz = (G >> 3) + ((grp < (G & 7u)) ? 1u : 0u);
;     const unsigned ngrp = G < 8u ? G : 8u;
;     __builtin_amdgcn_fence(__ATOMIC_RELEASE, "agent");
;     asm volatile("s_waitcnt vmcnt(0)" ::: "memory");
;     const unsigned old = __hip_atomic_fetch_add(bar + 64 * (1 + grp), 1u, __ATOMIC_RELAXED, __HIP_MEMORY_SCOPE_AGENT);
.LBB0_330:
	s_cmp_lt_i32 s95, 3
	s_cbranch_scc1 .LBB0_344
	s_and_b32 s99, s96, 7
	s_lshl_b32 s99, s99, 3
	s_add_u32 s99, s99, 0x1fe00080
	s_load_dwordx2 s[100:101], s[92:93], s99
	s_waitcnt vmcnt(0)
	v_sub_u32_e32 v0, 0, v195
	v_cmp_eq_u32_e32 vcc, s28, v0
	s_barrier
	s_and_saveexec_b64 s[0:1], vcc
	s_cbranch_execz .LBB0_343
	s_add_u32 s6, s92, 0x1fe00000
	s_mov_b64 s[4:5], exec
	s_addc_u32 s7, s93, 0
	s_and_b32 s10, s96, 7
	s_waitcnt lgkmcnt(0)
	s_add_u32 s98, s100, s101
	s_cmp_eq_u32 s98, 15
	s_cselect_b32 s98, 1, 0
	v_writelane_b32 v252, s98, 63
	s_cmp_eq_u32 s98, 1
	s_cbranch_scc1 .Lxg0
	buffer_wbl2 sc1

; DI void grid_barrier(const Ctx& c, unsigned idx) {
;     ...
;   asm volatile("s_waitcnt vmcnt(0)" ::: "memory");
;   __syncthreads();
;   if (TIDX == 0) {
;     unsigned* bar = (unsigned*)(p.ws + OFF_BAR);
;     const unsigned G = gridDim.x, grp = blockIdx.x & 7u;
;     const unsigned gsz = (G >> 3) + ((grp < (G & 7u)) ? 1u : 0u);
;     const unsigned ngrp = G < 8u ? G : 8u;
;     __builtin_amdgcn_fence(__ATOMIC_RELEASE, "agent");
;     asm volatile("s_waitcnt vmcnt(0)" ::: "memory");
;     const unsigned old = __hip_atomic_fetch_add(bar + 64 * (1 + grp), 1u, __ATOMIC_RELAXED, __HIP_MEMORY_SCOPE_AGENT);
.LBB0_535:
	s_or_b64 exec, exec, s[0:1]
	s_cmp_lt_i32 s95, 4
	s_cbranch_scc1 .LBB0_549
	s_waitcnt vmcnt(0)
	v_sub_u32_e32 v0, 0, v76
	v_cmp_eq_u32_e32 vcc, s21, v0
	s_barrier
	s_and_saveexec_b64 s[0:1], vcc
	s_cbranch_execz .LBB0_548
	s_add_u32 s6, s92, 0x1fe00000
	s_mov_b64 s[4:5], exec
	s_addc_u32 s7, s93, 0
	s_and_b32 s10, s96, 7
	v_readlane_b32 s98, v252, 63
	s_nop 3
	s_cmp_eq_u32 s98, 1
	s_cbranch_scc1 .Lxg1
	buffer_wbl2 sc1

; DI void grid_barrier(const Ctx& c, unsigned idx) {
;     ...
;   asm volatile("s_waitcnt vmcnt(0)" ::: "memory");
;   __syncthreads();
;   if (TIDX == 0) {
;     unsigned* bar = (unsigned*)(p.ws + OFF_BAR);
;     const unsigned G = gridDim.x, grp = blockIdx.x & 7u;
;     const unsigned gsz = (G >> 3) + ((grp < (G & 7u)) ? 1u : 0u);
;     const unsigned ngrp = G < 8u ? G : 8u;
;     __builtin_amdgcn_fence(__ATOMIC_RELEASE, "agent");
;     asm volatile("s_waitcnt vmcnt(0)" ::: "memory");
;     const unsigned old = __hip_atomic_fetch_add(bar + 64 * (1 + grp), 1u, __ATOMIC_RELAXED, __HIP_MEMORY_SCOPE_AGENT);
.LBB0_586:
	s_cmp_lt_u32 s95, 5
	s_cbranch_scc1 .LBB0_600
	s_waitcnt vmcnt(0)
	v_sub_u32_e32 v0, 0, v136
	v_cmp_eq_u32_e32 vcc, s14, v0
	s_waitcnt lgkmcnt(0)
	s_barrier
	s_and_saveexec_b64 s[0:1], vcc
	s_cbranch_execz .LBB0_599
	s_add_u32 s6, s92, 0x1fe00000
	s_mov_b64 s[4:5], exec
	s_addc_u32 s7, s93, 0
	s_and_b32 s10, s96, 7
	v_readlane_b32 s98, v252, 63
	s_nop 3
	s_cmp_eq_u32 s98, 1
	s_cbranch_scc1 .Lxg2
	buffer_wbl2 sc1

; DI void grid_barrier(const Ctx& c, unsigned idx) {
;     ...
;   asm volatile("s_waitcnt vmcnt(0)" ::: "memory");
;   __syncthreads();
;   if (TIDX == 0) {
;     unsigned* bar = (unsigned*)(p.ws + OFF_BAR);
;     const unsigned G = gridDim.x, grp = blockIdx.x & 7u;
;     const unsigned gsz = (G >> 3) + ((grp < (G & 7u)) ? 1u : 0u);
;     const unsigned ngrp = G < 8u ? G : 8u;
;     __builtin_amdgcn_fence(__ATOMIC_RELEASE, "agent");
;     asm volatile("s_waitcnt vmcnt(0)" ::: "memory");
;     const unsigned old = __hip_atomic_fetch_add(bar + 64 * (1 + grp), 1u, __ATOMIC_RELAXED, __HIP_MEMORY_SCOPE_AGENT);
.LBB0_813:
	s_waitcnt lgkmcnt(0)
	s_cmp_lt_i32 s95, 6
	s_cbranch_scc1 .LBB0_827
	s_waitcnt vmcnt(0)
	v_mbcnt_hi_u32_b32 v0, -1, v194
	s_and_b32 s0, s72, 0xffffffc0
	v_sub_u32_e32 v0, 0, v0
	v_cmp_eq_u32_e32 vcc, s0, v0
	s_barrier
	s_and_saveexec_b64 s[0:1], vcc
	s_cbranch_execz .LBB0_826
	s_add_u32 s6, s92, 0x1fe00000
	s_mov_b64 s[4:5], exec
	s_addc_u32 s7, s93, 0
	s_and_b32 s10, s96, 7
	v_readlane_b32 s98, v252, 63
	s_nop 3
	s_cmp_eq_u32 s98, 1
	s_cbranch_scc1 .Lxg3
	buffer_wbl2 sc1

; DI void grid_barrier(const Ctx& c, unsigned idx) {
;     ...
;   asm volatile("s_waitcnt vmcnt(0)" ::: "memory");
;   __syncthreads();
;   if (TIDX == 0) {
;     unsigned* bar = (unsigned*)(p.ws + OFF_BAR);
;     const unsigned G = gridDim.x, grp = blockIdx.x & 7u;
;     const unsigned gsz = (G >> 3) + ((grp < (G & 7u)) ? 1u : 0u);
;     const unsigned ngrp = G < 8u ? G : 8u;
;     __builtin_amdgcn_fence(__ATOMIC_RELEASE, "agent");
;     asm volatile("s_waitcnt vmcnt(0)" ::: "memory");
;     const unsigned old = __hip_atomic_fetch_add(bar + 64 * (1 + grp), 1u, __ATOMIC_RELAXED, __HIP_MEMORY_SCOPE_AGENT);
.LBB0_841:
	s_or_b64 exec, exec, s[0:1]
	s_cmp_lt_i32 s95, 7
	s_cbranch_scc1 .LBB0_855
	s_waitcnt vmcnt(0)
	v_sub_u32_e32 v0, 0, v81
	v_cmp_eq_u32_e32 vcc, s11, v0
	s_waitcnt lgkmcnt(0)
	s_barrier
	s_and_saveexec_b64 s[0:1], vcc
	s_cbranch_execz .LBB0_854
	s_add_u32 s6, s92, 0x1fe00000
	s_mov_b64 s[4:5], exec
	s_addc_u32 s7, s93, 0
	s_and_b32 s10, s96, 7
	v_readlane_b32 s98, v252, 63
	s_nop 3
	s_cmp_eq_u32 s98, 1
	s_cbranch_scc1 .Lxg4
	buffer_wbl2 sc1

; DI void grid_barrier(const Ctx& c, unsigned idx) {
;     ...
;   asm volatile("s_waitcnt vmcnt(0)" ::: "memory");
;   __syncthreads();
;   if (TIDX == 0) {
;     unsigned* bar = (unsigned*)(p.ws + OFF_BAR);
;     const unsigned G = gridDim.x, grp = blockIdx.x & 7u;
;     const unsigned gsz = (G >> 3) + ((grp < (G & 7u)) ? 1u : 0u);
;     const unsigned ngrp = G < 8u ? G : 8u;
;     __builtin_amdgcn_fence(__ATOMIC_RELEASE, "agent");
;     asm volatile("s_waitcnt vmcnt(0)" ::: "memory");
;     const unsigned old = __hip_atomic_fetch_add(bar + 64 * (1 + grp), 1u, __ATOMIC_RELAXED, __HIP_MEMORY_SCOPE_AGENT);
.LBB0_869:
	s_cmp_lt_i32 s95, 8
	s_cbranch_scc1 .LBB0_883
	s_waitcnt vmcnt(0)
	v_sub_u32_e32 v0, 0, v195
	v_cmp_eq_u32_e32 vcc, s8, v0
	s_barrier
	s_and_saveexec_b64 s[0:1], vcc
	s_cbranch_execz .LBB0_882
	s_add_u32 s6, s92, 0x1fe00000
	s_mov_b64 s[4:5], exec
	s_addc_u32 s7, s93, 0
	s_and_b32 s11, s96, 7
	v_readlane_b32 s98, v252, 63
	s_nop 3
	s_cmp_eq_u32 s98, 1
	s_cbranch_scc1 .Lxg5
	buffer_wbl2 sc1

; DI void grid_barrier(const Ctx& c, unsigned idx) {
;     ...
;   asm volatile("s_waitcnt vmcnt(0)" ::: "memory");
;   __syncthreads();
;   if (TIDX == 0) {
;     unsigned* bar = (unsigned*)(p.ws + OFF_BAR);
;     const unsigned G = gridDim.x, grp = blockIdx.x & 7u;
;     const unsigned gsz = (G >> 3) + ((grp < (G & 7u)) ? 1u : 0u);
;     const unsigned ngrp = G < 8u ? G : 8u;
;     __builtin_amdgcn_fence(__ATOMIC_RELEASE, "agent");
;     asm volatile("s_waitcnt vmcnt(0)" ::: "memory");
;     const unsigned old = __hip_atomic_fetch_add(bar + 64 * (1 + grp), 1u, __ATOMIC_RELAXED, __HIP_MEMORY_SCOPE_AGENT);
.LBB0_887:
	s_cmp_lt_u32 s95, 9
	s_cbranch_scc1 .LBB0_901
	s_waitcnt vmcnt(0)
	s_and_b32 s0, s72, 0xffffffc0
	v_sub_u32_e32 v0, 0, v35
	v_cmp_eq_u32_e32 vcc, s0, v0
	s_waitcnt lgkmcnt(0)
	s_barrier
	s_and_saveexec_b64 s[0:1], vcc
	s_cbranch_execz .LBB0_900
	s_add_u32 s4, s92, 0x1fe00000
	s_load_dword s12, s[74:75], 0x180
	s_mov_b64 s[6:7], exec
	s_addc_u32 s5, s93, 0
	s_and_b32 s10, s96, 7
	v_readlane_b32 s98, v252, 63
	s_nop 3
	s_cmp_eq_u32 s98, 1
	s_cbranch_scc1 .Lxg6
	buffer_wbl2 sc1

; DI void grid_barrier(const Ctx& c, unsigned idx) {
;     ...
;   asm volatile("s_waitcnt vmcnt(0)" ::: "memory");
;   __syncthreads();
;   if (TIDX == 0) {
;     unsigned* bar = (unsigned*)(p.ws + OFF_BAR);
;     const unsigned G = gridDim.x, grp = blockIdx.x & 7u;
;     const unsigned gsz = (G >> 3) + ((grp < (G & 7u)) ? 1u : 0u);
;     const unsigned ngrp = G < 8u ? G : 8u;
;     __builtin_amdgcn_fence(__ATOMIC_RELEASE, "agent");
;     asm volatile("s_waitcnt vmcnt(0)" ::: "memory");
;     const unsigned old = __hip_atomic_fetch_add(bar + 64 * (1 + grp), 1u, __ATOMIC_RELAXED, __HIP_MEMORY_SCOPE_AGENT);
.LBB0_915:
	s_cmp_lt_i32 s95, 10
	s_cbranch_scc1 .LBB0_929
	s_waitcnt vmcnt(0)
	v_sub_u32_e32 v0, 0, v195
	v_cmp_eq_u32_e32 vcc, s16, v0
	s_barrier
	s_and_saveexec_b64 s[0:1], vcc
	s_cbranch_execz .LBB0_928
	s_add_u32 s6, s92, 0x1fe00000
	s_mov_b64 s[4:5], exec
	s_addc_u32 s7, s93, 0
	s_and_b32 s10, s96, 7
	v_readlane_b32 s98, v252, 63
	s_nop 3
	s_cmp_eq_u32 s98, 1
	s_cbranch_scc1 .Lxg7
	buffer_wbl2 sc1

; DI void grid_barrier(const Ctx& c, unsigned idx) {
;     ...
;   asm volatile("s_waitcnt vmcnt(0)" ::: "memory");
;   __syncthreads();
;   if (TIDX == 0) {
;     unsigned* bar = (unsigned*)(p.ws + OFF_BAR);
;     const unsigned G = gridDim.x, grp = blockIdx.x & 7u;
;     const unsigned gsz = (G >> 3) + ((grp < (G & 7u)) ? 1u : 0u);
;     const unsigned ngrp = G < 8u ? G : 8u;
;     __builtin_amdgcn_fence(__ATOMIC_RELEASE, "agent");
;     asm volatile("s_waitcnt vmcnt(0)" ::: "memory");
;     const unsigned old = __hip_atomic_fetch_add(bar + 64 * (1 + grp), 1u, __ATOMIC_RELAXED, __HIP_MEMORY_SCOPE_AGENT);
.LBB0_943:
	s_cmp_lt_i32 s95, 11
	s_cbranch_scc1 .LBB0_957
	s_waitcnt vmcnt(0)
	v_sub_u32_e32 v0, 0, v195
	v_cmp_eq_u32_e32 vcc, s14, v0
	s_barrier
	s_and_saveexec_b64 s[0:1], vcc
	s_cbranch_execz .LBB0_956
	s_add_u32 s6, s92, 0x1fe00000
	s_mov_b64 s[4:5], exec
	s_addc_u32 s7, s93, 0
	s_and_b32 s10, s96, 7
	v_readlane_b32 s98, v252, 63
	s_nop 3
	s_cmp_eq_u32 s98, 1
	s_cbranch_scc1 .Lxg8
	buffer_wbl2 sc1

; DI void grid_barrier(const Ctx& c, unsigned idx) {
;     ...
;   asm volatile("s_waitcnt vmcnt(0)" ::: "memory");
;   __syncthreads();
;   if (TIDX == 0) {
;     unsigned* bar = (unsigned*)(p.ws + OFF_BAR);
;     const unsigned G = gridDim.x, grp = blockIdx.x & 7u;
;     const unsigned gsz = (G >> 3) + ((grp < (G & 7u)) ? 1u : 0u);
;     const unsigned ngrp = G < 8u ? G : 8u;
;     __builtin_amdgcn_fence(__ATOMIC_RELEASE, "agent");
;     asm volatile("s_waitcnt vmcnt(0)" ::: "memory");
;     const unsigned old = __hip_atomic_fetch_add(bar + 64 * (1 + grp), 1u, __ATOMIC_RELAXED, __HIP_MEMORY_SCOPE_AGENT);
.LBB0_961:
	s_cmp_lt_u32 s95, 12
	s_cbranch_scc1 .LBB0_975
	s_waitcnt vmcnt(0)
	s_and_b32 s0, s72, 0xffffffc0
	v_sub_u32_e32 v0, 0, v35
	v_cmp_eq_u32_e32 vcc, s0, v0
	s_waitcnt lgkmcnt(0)
	s_barrier
	s_and_saveexec_b64 s[0:1], vcc
	s_cbranch_execz .LBB0_974
	s_add_u32 s4, s92, 0x1fe00000
	s_load_dword s12, s[74:75], 0x180
	s_mov_b64 s[6:7], exec
	s_addc_u32 s5, s93, 0
	s_and_b32 s10, s96, 7
	v_readlane_b32 s98, v252, 63
	s_nop 3
	s_cmp_eq_u32 s98, 1
	s_cbranch_scc1 .Lxg9
	buffer_wbl2 sc1

; DI void grid_barrier(const Ctx& c, unsigned idx) {
;     ...
;   asm volatile("s_waitcnt vmcnt(0)" ::: "memory");
;   __syncthreads();
;   if (TIDX == 0) {
;     unsigned* bar = (unsigned*)(p.ws + OFF_BAR);
;     const unsigned G = gridDim.x, grp = blockIdx.x & 7u;
;     const unsigned gsz = (G >> 3) + ((grp < (G & 7u)) ? 1u : 0u);
;     const unsigned ngrp = G < 8u ? G : 8u;
;     __builtin_amdgcn_fence(__ATOMIC_RELEASE, "agent");
;     asm volatile("s_waitcnt vmcnt(0)" ::: "memory");
;     const unsigned old = __hip_atomic_fetch_add(bar + 64 * (1 + grp), 1u, __ATOMIC_RELAXED, __HIP_MEMORY_SCOPE_AGENT);
.LBB0_1245:
	s_cmp_lt_i32 s95, 13
	s_cbranch_scc1 .LBB0_1259
	s_waitcnt vmcnt(0)
	v_sub_u32_e32 v0, 0, v195
	v_cmp_eq_u32_e32 vcc, s36, v0
	s_barrier
	s_and_saveexec_b64 s[0:1], vcc
	s_cbranch_execz .LBB0_1258
	s_add_u32 s6, s92, 0x1fe00000
	s_mov_b64 s[4:5], exec
	s_addc_u32 s7, s93, 0
	s_and_b32 s10, s96, 7
	v_readlane_b32 s98, v252, 63
	s_nop 3
	s_cmp_eq_u32 s98, 1
	s_cbranch_scc1 .Lxg10
	buffer_wbl2 sc1

; DI void grid_barrier(const Ctx& c, unsigned idx) {
;     ...
;   asm volatile("s_waitcnt vmcnt(0)" ::: "memory");
;   __syncthreads();
;   if (TIDX == 0) {
;     unsigned* bar = (unsigned*)(p.ws + OFF_BAR);
;     const unsigned G = gridDim.x, grp = blockIdx.x & 7u;
;     const unsigned gsz = (G >> 3) + ((grp < (G & 7u)) ? 1u : 0u);
;     const unsigned ngrp = G < 8u ? G : 8u;
;     __builtin_amdgcn_fence(__ATOMIC_RELEASE, "agent");
;     asm volatile("s_waitcnt vmcnt(0)" ::: "memory");
;     const unsigned old = __hip_atomic_fetch_add(bar + 64 * (1 + grp), 1u, __ATOMIC_RELAXED, __HIP_MEMORY_SCOPE_AGENT);
.LBB0_1710:
	s_cmp_lt_i32 s95, 14
	s_cbranch_scc1 .LBB0_1724
	s_waitcnt vmcnt(0)
	v_mbcnt_hi_u32_b32 v0, -1, v194
	s_and_b32 s0, s72, 0xffffffc0
	v_sub_u32_e32 v0, 0, v0
	v_cmp_eq_u32_e32 vcc, s0, v0
	s_barrier
	s_and_saveexec_b64 s[0:1], vcc
	s_cbranch_execz .LBB0_1723
	s_add_u32 s6, s92, 0x1fe00000
	s_mov_b64 s[4:5], exec
	s_addc_u32 s7, s93, 0
	s_and_b32 s10, s96, 7
	v_readlane_b32 s98, v252, 63
	s_nop 3
	s_cmp_eq_u32 s98, 1
	s_cbranch_scc1 .Lxg11
	buffer_wbl2 sc1

; DI void grid_barrier(const Ctx& c, unsigned idx) {
;     ...
;   asm volatile("s_waitcnt vmcnt(0)" ::: "memory");
;   __syncthreads();
;   if (TIDX == 0) {
;     unsigned* bar = (unsigned*)(p.ws + OFF_BAR);
;     const unsigned G = gridDim.x, grp = blockIdx.x & 7u;
;     const unsigned gsz = (G >> 3) + ((grp < (G & 7u)) ? 1u : 0u);
;     const unsigned ngrp = G < 8u ? G : 8u;
;     __builtin_amdgcn_fence(__ATOMIC_RELEASE, "agent");
;     asm volatile("s_waitcnt vmcnt(0)" ::: "memory");
;     const unsigned old = __hip_atomic_fetch_add(bar + 64 * (1 + grp), 1u, __ATOMIC_RELAXED, __HIP_MEMORY_SCOPE_AGENT);
.LBB0_1802:
	s_or_b64 exec, exec, s[0:1]
	s_cmp_lt_i32 s95, 15
	s_cbranch_scc1 .LBB0_1816
	s_waitcnt vmcnt(0)
	v_sub_u32_e32 v0, 0, v81
	v_cmp_eq_u32_e32 vcc, s16, v0
	s_waitcnt lgkmcnt(0)
	s_barrier
	s_and_saveexec_b64 s[0:1], vcc
	s_cbranch_execz .LBB0_1815
	s_add_u32 s6, s92, 0x1fe00000
	s_mov_b64 s[4:5], exec
	s_addc_u32 s7, s93, 0
	s_and_b32 s10, s96, 7
	v_readlane_b32 s98, v252, 63
	s_nop 3
	s_cmp_eq_u32 s98, 1
	s_cbranch_scc1 .Lxg12
	buffer_wbl2 sc1

; DI void grid_barrier(const Ctx& c, unsigned idx) {
;     ...
;   asm volatile("s_waitcnt vmcnt(0)" ::: "memory");
;   __syncthreads();
;   if (TIDX == 0) {
;     unsigned* bar = (unsigned*)(p.ws + OFF_BAR);
;     const unsigned G = gridDim.x, grp = blockIdx.x & 7u;
;     const unsigned gsz = (G >> 3) + ((grp < (G & 7u)) ? 1u : 0u);
;     const unsigned ngrp = G < 8u ? G : 8u;
;     __builtin_amdgcn_fence(__ATOMIC_RELEASE, "agent");
;     asm volatile("s_waitcnt vmcnt(0)" ::: "memory");
;     const unsigned old = __hip_atomic_fetch_add(bar + 64 * (1 + grp), 1u, __ATOMIC_RELAXED, __HIP_MEMORY_SCOPE_AGENT);
.LBB0_1830:
	s_cmp_lt_i32 s95, 16
	s_cbranch_scc1 .LBB0_1844
	s_waitcnt vmcnt(0)
	v_sub_u32_e32 v0, 0, v195
	v_cmp_eq_u32_e32 vcc, s16, v0
	s_barrier
	s_and_saveexec_b64 s[0:1], vcc
	s_cbranch_execz .LBB0_1843
	s_add_u32 s6, s92, 0x1fe00000
	s_mov_b64 s[4:5], exec
	s_addc_u32 s7, s93, 0
	s_and_b32 s10, s96, 7
	v_readlane_b32 s98, v252, 63
	s_nop 3
	s_cmp_eq_u32 s98, 1
	s_cbranch_scc1 .Lxg13
	buffer_wbl2 sc1

; DI void grid_barrier(const Ctx& c, unsigned idx) {
;     ...
;   asm volatile("s_waitcnt vmcnt(0)" ::: "memory");
;   __syncthreads();
;   if (TIDX == 0) {
;     unsigned* bar = (unsigned*)(p.ws + OFF_BAR);
;     const unsigned G = gridDim.x, grp = blockIdx.x & 7u;
;     const unsigned gsz = (G >> 3) + ((grp < (G & 7u)) ? 1u : 0u);
;     const unsigned ngrp = G < 8u ? G : 8u;
;     __builtin_amdgcn_fence(__ATOMIC_RELEASE, "agent");
;     asm volatile("s_waitcnt vmcnt(0)" ::: "memory");
;     const unsigned old = __hip_atomic_fetch_add(bar + 64 * (1 + grp), 1u, __ATOMIC_RELAXED, __HIP_MEMORY_SCOPE_AGENT);
.LBB0_1858:
	s_cmp_lt_i32 s95, 17
	s_cbranch_scc1 .LBB0_1872
	s_waitcnt vmcnt(0)
	v_sub_u32_e32 v0, 0, v195
	v_cmp_eq_u32_e32 vcc, s8, v0
	s_barrier
	s_and_saveexec_b64 s[0:1], vcc
	s_cbranch_execz .LBB0_1871
	s_add_u32 s6, s92, 0x1fe00000
	s_mov_b64 s[4:5], exec
	s_addc_u32 s7, s93, 0
	s_and_b32 s11, s96, 7
	v_readlane_b32 s98, v252, 63
	s_nop 3
	s_cmp_eq_u32 s98, 1
	s_cbranch_scc1 .Lxg14
	buffer_wbl2 sc1

; DI void grid_barrier(const Ctx& c, unsigned idx) {
;     ...
;   asm volatile("s_waitcnt vmcnt(0)" ::: "memory");
;   __syncthreads();
;   if (TIDX == 0) {
;     unsigned* bar = (unsigned*)(p.ws + OFF_BAR);
;     const unsigned G = gridDim.x, grp = blockIdx.x & 7u;
;     const unsigned gsz = (G >> 3) + ((grp < (G & 7u)) ? 1u : 0u);
;     const unsigned ngrp = G < 8u ? G : 8u;
;     __builtin_amdgcn_fence(__ATOMIC_RELEASE, "agent");
;     asm volatile("s_waitcnt vmcnt(0)" ::: "memory");
;     const unsigned old = __hip_atomic_fetch_add(bar + 64 * (1 + grp), 1u, __ATOMIC_RELAXED, __HIP_MEMORY_SCOPE_AGENT);
.LBB0_1876:
	s_cmp_lt_u32 s95, 18
	s_cbranch_scc1 .LBB0_1890
	s_waitcnt vmcnt(0)
	s_and_b32 s0, s72, 0xffffffc0
	v_sub_u32_e32 v0, 0, v35
	v_cmp_eq_u32_e32 vcc, s0, v0
	s_waitcnt lgkmcnt(0)
	s_barrier
	s_and_saveexec_b64 s[0:1], vcc
	s_cbranch_execz .LBB0_1889
	s_add_u32 s4, s92, 0x1fe00000
	s_load_dword s12, s[74:75], 0x180
	s_mov_b64 s[6:7], exec
	s_addc_u32 s5, s93, 0
	s_and_b32 s10, s96, 7
	v_readlane_b32 s98, v252, 63
	s_nop 3
	s_cmp_eq_u32 s98, 1
	s_cbranch_scc1 .Lxg15
	buffer_wbl2 sc1

; DI void grid_barrier(const Ctx& c, unsigned idx) {
;     ...
;   asm volatile("s_waitcnt vmcnt(0)" ::: "memory");
;   __syncthreads();
;   if (TIDX == 0) {
;     unsigned* bar = (unsigned*)(p.ws + OFF_BAR);
;     const unsigned G = gridDim.x, grp = blockIdx.x & 7u;
;     const unsigned gsz = (G >> 3) + ((grp < (G & 7u)) ? 1u : 0u);
;     const unsigned ngrp = G < 8u ? G : 8u;
;     __builtin_amdgcn_fence(__ATOMIC_RELEASE, "agent");
;     asm volatile("s_waitcnt vmcnt(0)" ::: "memory");
;     const unsigned old = __hip_atomic_fetch_add(bar + 64 * (1 + grp), 1u, __ATOMIC_RELAXED, __HIP_MEMORY_SCOPE_AGENT);
.LBB0_1904:
	s_cmp_lt_i32 s95, 19
	s_cbranch_scc1 .LBB0_1918
	s_waitcnt vmcnt(0)
	v_sub_u32_e32 v0, 0, v195
	v_cmp_eq_u32_e32 vcc, s16, v0
	s_barrier
	s_and_saveexec_b64 s[0:1], vcc
	s_cbranch_execz .LBB0_1917
	s_add_u32 s6, s92, 0x1fe00000
	s_mov_b64 s[4:5], exec
	s_addc_u32 s7, s93, 0
	s_and_b32 s10, s96, 7
	v_readlane_b32 s98, v252, 63
	s_nop 3
	s_cmp_eq_u32 s98, 1
	s_cbranch_scc1 .Lxg16
	buffer_wbl2 sc1

; DI void grid_barrier(const Ctx& c, unsigned idx) {
;   const Params& p = c.p; (void)p;
;   asm volatile("s_waitcnt vmcnt(0)" ::: "memory");
;   __syncthreads();
;   if (TIDX == 0) {
;     unsigned* bar = (unsigned*)(p.ws + OFF_BAR);
;     const unsigned G = gridDim.x, grp = blockIdx.x & 7u;
;     const unsigned gsz = (G >> 3) + ((grp < (G & 7u)) ? 1u : 0u);
;     const unsigned ngrp = G < 8u ? G : 8u;
;     __builtin_amdgcn_fence(__ATOMIC_RELEASE, "agent");
;     asm volatile("s_waitcnt vmcnt(0)" ::: "memory");
;     const unsigned old = __hip_atomic_fetch_add(bar + 64 * (1 + grp), 1u, __ATOMIC_RELAXED, __HIP_MEMORY_SCOPE_AGENT);
;     if (old + 1u == idx * gsz) {
.LBB0_1932:
	s_cmp_lt_i32 s95, 20
	s_cbranch_scc1 .LBB0_1946
	s_waitcnt vmcnt(0)
	v_sub_u32_e32 v0, 0, v195
	v_cmp_eq_u32_e32 vcc, s14, v0
	s_barrier
	s_and_saveexec_b64 s[0:1], vcc
	s_cbranch_execz .LBB0_1945
	s_add_u32 s6, s92, 0x1fe00000
	s_mov_b64 s[4:5], exec
	s_addc_u32 s7, s93, 0
	s_and_b32 s10, s96, 7
	v_readlane_b32 s98, v252, 63
	s_nop 3
	s_cmp_eq_u32 s98, 1
	s_cbranch_scc1 .Lxg17
	buffer_wbl2 sc1

; DI void grid_barrier(const Ctx& c, unsigned idx) {
;   const Params& p = c.p; (void)p;
;   asm volatile("s_waitcnt vmcnt(0)" ::: "memory");
;   __syncthreads();
;   if (TIDX == 0) {
;     unsigned* bar = (unsigned*)(p.ws + OFF_BAR);
;     const unsigned G = gridDim.x, grp = blockIdx.x & 7u;
;     const unsigned gsz = (G >> 3) + ((grp < (G & 7u)) ? 1u : 0u);
;     const unsigned ngrp = G < 8u ? G : 8u;
;     __builtin_amdgcn_fence(__ATOMIC_RELEASE, "agent");
;     asm volatile("s_waitcnt vmcnt(0)" ::: "memory");
;     const unsigned old = __hip_atomic_fetch_add(bar + 64 * (1 + grp), 1u, __ATOMIC_RELAXED, __HIP_MEMORY_SCOPE_AGENT);
;     if (old + 1u == idx * gsz) {
.LBB0_1950:
	s_cmp_lt_u32 s95, 21
	s_cbranch_scc1 .LBB0_1964
	s_waitcnt vmcnt(0)
	s_and_b32 s0, s72, 0xffffffc0
	v_sub_u32_e32 v0, 0, v21
	v_cmp_eq_u32_e32 vcc, s0, v0
	s_waitcnt lgkmcnt(0)
	s_barrier
	s_and_saveexec_b64 s[0:1], vcc
	s_cbranch_execz .LBB0_1963
	s_add_u32 s4, s92, 0x1fe00000
	s_load_dword s12, s[74:75], 0x180
	s_mov_b64 s[6:7], exec
	s_addc_u32 s5, s93, 0
	s_and_b32 s10, s96, 7
	v_readlane_b32 s98, v252, 63
	s_nop 3
	s_cmp_eq_u32 s98, 1
	s_cbranch_scc1 .Lxg18
	buffer_wbl2 sc1
